# attention: the same dead-instruction deletions (canonicalizing v_max pairs, +0 adds, max-chain heads) applied to the band/diagonal tile blocks too; placement of later loops kept by padding
# baseline (speedup 1.0000x reference)
;   #define RESC() do{ if(resc){ asm volatile("s_waitcnt lgkmcnt(0)":::"memory"); \
;       _Pragma("unroll") for(int d_=0;d_<2;++d_) _Pragma("unroll") for(int r=0;r<16;++r)o[d_][r]*=wsf[crow(r,hi)]; } }while(0)
;   #define ROT() do{sl_prev=sl_cur;sl_cur=sl_next;sl_next=(sl_next==(NSLOT-1)*SLOTB)?0:sl_next+SLOTB;}while(0)
;   #define ENDW(tt) do{ if((tt)+3<NT){WAIT_BAR(2);} else if((tt)+2<NT){WAIT_BAR(1);} else {WAIT_BAR(0);} }while(0)
; template<int THRL> __device__ __forceinline__ void attn_unit(int b,int h,int qb,const bf16*Q,const bf16*__restrict__ K,const bf16*__restrict__ V,bf16*O,char*shm){
;     ...
;   for(;t+1<NT;t+=2){
;     STEP(pB0,pB1,pA0,pA1,t,(t+3<NT),(t+1<NT),(t+1<NT));       ENDW(t);   RESC(); ROT();
;     STEP(pA0,pA1,pB0,pB1,t+1,(t+4<NT),(t+2<NT),(t+2<NT));     ENDW(t+1); RESC(); ROT();
.LBB0_580:
	v_add_u32_e32 v4, s16, v194
	ds_read_b64_tr_b16 v[168:169], v4 offset:24576
	ds_read_b64_tr_b16 v[170:171], v4 offset:25088
	s_waitcnt lgkmcnt(5)
	v_mfma_f32_32x32x16_bf16 v[112:127], v[164:167], v[144:147], v[48:63]
	v_add_f32_e32 v2, v80, v81
	v_add_f32_e32 v2, v82, v2
	v_add_f32_e32 v2, v83, v2
	v_add_f32_e32 v2, v84, v2
	v_add_f32_e32 v2, v85, v2
	v_cvt_pk_bf16_f32 v148, v80, v81
	v_cvt_pk_bf16_f32 v149, v82, v83
	ds_read_b64_tr_b16 v[164:165], v4 offset:28672
	ds_read_b64_tr_b16 v[166:167], v4 offset:29184
	s_waitcnt lgkmcnt(6)
	v_mfma_f32_32x32x16_bf16 v[96:111], v[160:163], v[144:147], v[48:63]
	v_add_f32_e32 v2, v86, v2
	v_add_f32_e32 v2, v87, v2
	v_add_f32_e32 v2, v88, v2
	v_add_f32_e32 v2, v89, v2
	v_cvt_pk_bf16_f32 v150, v84, v85
	v_cvt_pk_bf16_f32 v151, v86, v87
	ds_read_b64_tr_b16 v[6:7], v4 offset:25600
	ds_read_b64_tr_b16 v[8:9], v4 offset:26112
	s_waitcnt lgkmcnt(7)
	v_mfma_f32_32x32x16_bf16 v[112:127], v[156:159], v[136:139], v[112:127]
	v_add_f32_e32 v2, v90, v2
	v_add_f32_e32 v2, v91, v2
	v_add_f32_e32 v2, v92, v2
	v_add_f32_e32 v2, v93, v2
	v_cvt_pk_bf16_f32 v140, v88, v89
	v_cvt_pk_bf16_f32 v141, v90, v91
	ds_read_b64_tr_b16 v[80:81], v4 offset:29696
	ds_read_b64_tr_b16 v[82:83], v4 offset:30208
	s_waitcnt lgkmcnt(8)
	v_mfma_f32_32x32x16_bf16 v[96:111], v[152:155], v[136:139], v[96:111]
	v_add_f32_e32 v2, v94, v2
	v_add_f32_e32 v2, v95, v2
	v_add_f32_e32 v2, v64, v2
	v_add_f32_e32 v2, v65, v2
	v_cvt_pk_bf16_f32 v142, v92, v93
	v_cvt_pk_bf16_f32 v143, v94, v95
	ds_read_b64_tr_b16 v[84:85], v4 offset:26624
	ds_read_b64_tr_b16 v[86:87], v4 offset:27136
	v_add_f32_e32 v2, v66, v2
	v_add_f32_e32 v2, v67, v2
	v_add_f32_e32 v2, v68, v2
	v_add_f32_e32 v2, v69, v2
	v_cvt_pk_bf16_f32 v132, v64, v65
	v_cvt_pk_bf16_f32 v133, v66, v67
	ds_read_b64_tr_b16 v[64:65], v4 offset:30720
	ds_read_b64_tr_b16 v[66:67], v4 offset:31232
	v_add_f32_e32 v2, v70, v2
	v_add_f32_e32 v2, v71, v2
	v_add_f32_e32 v2, v72, v2
	v_add_f32_e32 v2, v73, v2
	v_cvt_pk_bf16_f32 v134, v68, v69
	v_cvt_pk_bf16_f32 v135, v70, v71
	ds_read_b64_tr_b16 v[10:11], v4 offset:27648
	ds_read_b64_tr_b16 v[12:13], v4 offset:28160
	v_add_f32_e32 v2, v74, v2
	v_add_f32_e32 v2, v75, v2
	v_add_f32_e32 v2, v76, v2
	v_add_f32_e32 v68, v77, v2
	v_cvt_pk_bf16_f32 v128, v72, v73
	v_cvt_pk_bf16_f32 v129, v74, v75
	ds_read_b64_tr_b16 v[2:3], v4 offset:31744
	ds_read_b64_tr_b16 v[4:5], v4 offset:32256
	v_add_f32_e32 v68, v78, v68
	v_add_f32_e32 v68, v79, v68
	v_cvt_pk_bf16_f32 v130, v76, v77
	v_cvt_pk_bf16_f32 v131, v78, v79
	s_add_i32 s3, s18, 1
	s_cmp_ge_i32 s3, s77
	s_cselect_b64 s[14:15], -1, 0
	s_and_b64 vcc, exec, s[14:15]
	s_cbranch_vccnz .LBB0_582
	s_add_i32 s3, s78, s75
	v_lshl_add_u64 v[70:71], v[180:181], 0, s[50:51]
	s_mov_b32 s6, m0
	s_mov_b32 m0, s3
	s_nop 0
	global_load_lds_dwordx4 v[70:71], off
	s_mov_b32 m0, s6

.LBB0_584:
	v_add_f32_e32 v196, v196, v68
	v_max_f32_e32 v68, v112, v113
	v_max3_f32 v69, v114, v115, v97
	v_max3_f32 v68, v68, v96, v98
	v_max3_f32 v68, v68, v99, v116
	v_max3_f32 v69, v69, v118, v119
	v_max3_f32 v68, v68, v117, v100
	v_max3_f32 v69, v69, v102, v103
	v_max3_f32 v68, v68, v101, v120
	v_max3_f32 v69, v69, v122, v123
	v_max3_f32 v68, v68, v121, v104
	v_max3_f32 v69, v69, v106, v107
	v_max3_f32 v68, v68, v105, v124
	v_max3_f32 v69, v69, v126, v127
	v_max3_f32 v68, v68, v125, v108
	v_max3_f32 v69, v69, v110, v111
	v_max3_f32 v68, v68, v109, v69
	v_mov_b32_e32 v69, v68
	s_nop 1
	v_permlane32_swap_b32_e32 v68, v69
	v_max_f32_e32 v68, v68, v69
	v_cmp_lt_f32_e32 vcc, s58, v68
	s_cmp_lg_u64 vcc, 0
	s_cselect_b64 s[6:7], -1, 0
	s_cbranch_vccnz .LBB0_618

;   #define RESC() do{ if(resc){ asm volatile("s_waitcnt lgkmcnt(0)":::"memory"); \
;       _Pragma("unroll") for(int d_=0;d_<2;++d_) _Pragma("unroll") for(int r=0;r<16;++r)o[d_][r]*=wsf[crow(r,hi)]; } }while(0)
;   #define ROT() do{sl_prev=sl_cur;sl_cur=sl_next;sl_next=(sl_next==(NSLOT-1)*SLOTB)?0:sl_next+SLOTB;}while(0)
;   #define ENDW(tt) do{ if((tt)+3<NT){WAIT_BAR(2);} else if((tt)+2<NT){WAIT_BAR(1);} else {WAIT_BAR(0);} }while(0)
; template<int THRL> __device__ __forceinline__ void attn_unit(int b,int h,int qb,const bf16*Q,const bf16*__restrict__ K,const bf16*__restrict__ V,bf16*O,char*shm){
;     ...
;     STEP(pA0,pA1,pB0,pB1,t+1,(t+4<NT),(t+2<NT),(t+2<NT));     ENDW(t+1); RESC(); ROT();
.LBB0_593:
	v_add_u32_e32 v4, s78, v194
	ds_read_b64_tr_b16 v[176:177], v4 offset:24576
	ds_read_b64_tr_b16 v[178:179], v4 offset:25088
	s_waitcnt lgkmcnt(5)
	v_mfma_f32_32x32x16_bf16 v[80:95], v[164:167], v[144:147], v[48:63]
	v_add_f32_e32 v2, v112, v113
	v_add_f32_e32 v2, v114, v2
	v_add_f32_e32 v2, v115, v2
	v_add_f32_e32 v2, v116, v2
	v_add_f32_e32 v2, v117, v2
	v_cvt_pk_bf16_f32 v148, v112, v113
	v_cvt_pk_bf16_f32 v149, v114, v115
	ds_read_b64_tr_b16 v[172:173], v4 offset:28672
	ds_read_b64_tr_b16 v[174:175], v4 offset:29184
	s_waitcnt lgkmcnt(6)
	v_mfma_f32_32x32x16_bf16 v[64:79], v[160:163], v[144:147], v[48:63]
	v_add_f32_e32 v2, v118, v2
	v_add_f32_e32 v2, v119, v2
	v_add_f32_e32 v2, v120, v2
	v_add_f32_e32 v2, v121, v2
	v_cvt_pk_bf16_f32 v150, v116, v117
	v_cvt_pk_bf16_f32 v151, v118, v119
	ds_read_b64_tr_b16 v[168:169], v4 offset:25600
	ds_read_b64_tr_b16 v[170:171], v4 offset:26112
	s_waitcnt lgkmcnt(7)
	v_mfma_f32_32x32x16_bf16 v[80:95], v[156:159], v[136:139], v[80:95]
	v_add_f32_e32 v2, v122, v2
	v_add_f32_e32 v2, v123, v2
	v_add_f32_e32 v2, v124, v2
	v_add_f32_e32 v2, v125, v2
	v_cvt_pk_bf16_f32 v140, v120, v121
	v_cvt_pk_bf16_f32 v141, v122, v123
	ds_read_b64_tr_b16 v[116:117], v4 offset:29696
	ds_read_b64_tr_b16 v[118:119], v4 offset:30208
	s_waitcnt lgkmcnt(8)
	v_mfma_f32_32x32x16_bf16 v[64:79], v[152:155], v[136:139], v[64:79]
	v_add_f32_e32 v2, v126, v2
	v_add_f32_e32 v2, v127, v2
	v_add_f32_e32 v2, v96, v2
	v_add_f32_e32 v2, v97, v2
	v_cvt_pk_bf16_f32 v142, v124, v125
	v_cvt_pk_bf16_f32 v143, v126, v127
	ds_read_b64_tr_b16 v[112:113], v4 offset:26624
	ds_read_b64_tr_b16 v[114:115], v4 offset:27136
	v_add_f32_e32 v2, v98, v2
	v_add_f32_e32 v2, v99, v2
	v_add_f32_e32 v2, v100, v2
	v_add_f32_e32 v2, v101, v2
	v_cvt_pk_bf16_f32 v132, v96, v97
	v_cvt_pk_bf16_f32 v133, v98, v99
	ds_read_b64_tr_b16 v[10:11], v4 offset:30720
	ds_read_b64_tr_b16 v[12:13], v4 offset:31232
	v_add_f32_e32 v2, v102, v2
	v_add_f32_e32 v2, v103, v2
	v_add_f32_e32 v2, v104, v2
	v_add_f32_e32 v2, v105, v2
	v_cvt_pk_bf16_f32 v134, v100, v101
	v_cvt_pk_bf16_f32 v135, v102, v103
	ds_read_b64_tr_b16 v[6:7], v4 offset:27648
	ds_read_b64_tr_b16 v[8:9], v4 offset:28160
	v_add_f32_e32 v2, v106, v2
	v_add_f32_e32 v2, v107, v2
	v_add_f32_e32 v2, v108, v2
	v_add_f32_e32 v96, v109, v2
	v_cvt_pk_bf16_f32 v128, v104, v105
	v_cvt_pk_bf16_f32 v129, v106, v107
	ds_read_b64_tr_b16 v[2:3], v4 offset:31744
	ds_read_b64_tr_b16 v[4:5], v4 offset:32256
	v_add_f32_e32 v96, v110, v96
	v_add_f32_e32 v96, v111, v96
	v_cvt_pk_bf16_f32 v130, v108, v109
	v_cvt_pk_bf16_f32 v131, v110, v111
	s_add_i32 s30, s18, 2
	s_cmp_ge_i32 s30, s77
	s_cselect_b64 s[16:17], -1, 0
	s_and_b64 vcc, exec, s[16:17]
	s_cbranch_vccnz .LBB0_595
	s_add_i32 s6, s38, s75
	s_mov_b32 s7, m0
	s_mov_b32 m0, s6
	s_nop 0
	global_load_lds_dwordx4 v[180:181], off
	s_mov_b32 m0, s7

.LBB0_599:
	v_add_f32_e32 v196, v196, v96
	v_max_f32_e32 v96, v80, v81
	v_max3_f32 v97, v82, v83, v65
	v_max3_f32 v96, v96, v64, v66
	v_max3_f32 v96, v96, v67, v84
	v_max3_f32 v97, v97, v86, v87
	v_max3_f32 v96, v96, v85, v68
	v_max3_f32 v97, v97, v70, v71
	v_max3_f32 v96, v96, v69, v88
	v_max3_f32 v97, v97, v90, v91
	v_max3_f32 v96, v96, v89, v72
	v_max3_f32 v97, v97, v74, v75
	v_max3_f32 v96, v96, v73, v92
	v_max3_f32 v97, v97, v94, v95
	v_max3_f32 v96, v96, v93, v76
	v_max3_f32 v97, v97, v78, v79
	v_max3_f32 v96, v96, v77, v97
	v_mov_b32_e32 v97, v96
	s_nop 1
	v_permlane32_swap_b32_e32 v96, v97
	v_max_f32_e32 v96, v96, v97
	v_cmp_lt_f32_e32 vcc, s58, v96
	s_cmp_lg_u64 vcc, 0
	s_cselect_b64 s[18:19], -1, 0
	s_cbranch_vccnz .LBB0_621

; __device__ __forceinline__ void cmask(f32x16&p0,f32x16&p1,int jb,int qrel,int hi){
;   const float NEG=-INFINITY; int kb=64*jb+4*hi;
;   #pragma unroll
;   for(int r=0;r<16;++r){int kv=kb+(r&3)+8*(r>>2); if(kv>qrel)p0[r]=NEG; if(kv+32>qrel)p1[r]=NEG;}
; }
.LBB0_625:
	v_add_u32_e32 v0, s38, v194
	ds_read_b64_tr_b16 v[6:7], v0 offset:24576
	ds_read_b64_tr_b16 v[8:9], v0 offset:25088
	v_add_f32_e32 v2, v80, v81
	v_add_f32_e32 v2, v82, v2
	v_add_f32_e32 v2, v83, v2
	v_add_f32_e32 v2, v84, v2
	v_add_f32_e32 v10, v85, v2
	v_cvt_pk_bf16_f32 v148, v80, v81
	v_cvt_pk_bf16_f32 v149, v82, v83
	s_waitcnt lgkmcnt(5)
	v_mfma_f32_32x32x16_bf16 v[96:111], v[164:167], v[144:147], v[48:63]
	ds_read_b64_tr_b16 v[2:3], v0 offset:28672
	ds_read_b64_tr_b16 v[4:5], v0 offset:29184
	s_waitcnt lgkmcnt(6)
	v_mfma_f32_32x32x16_bf16 v[48:63], v[160:163], v[144:147], v[48:63]
	v_add_f32_e32 v10, v86, v10
	v_add_f32_e32 v10, v87, v10
	v_add_f32_e32 v10, v88, v10
	v_add_f32_e32 v10, v89, v10
	v_cvt_pk_bf16_f32 v150, v84, v85
	v_cvt_pk_bf16_f32 v151, v86, v87
	ds_read_b64_tr_b16 v[112:113], v0 offset:25600
	ds_read_b64_tr_b16 v[114:115], v0 offset:26112
	v_add_f32_e32 v10, v90, v10
	v_add_f32_e32 v10, v91, v10
	v_add_f32_e32 v10, v92, v10
	v_add_f32_e32 v10, v93, v10
	v_cvt_pk_bf16_f32 v140, v88, v89
	v_cvt_pk_bf16_f32 v141, v90, v91
	s_waitcnt lgkmcnt(7)
	v_mfma_f32_32x32x16_bf16 v[96:111], v[156:159], v[136:139], v[96:111]
	ds_read_b64_tr_b16 v[120:121], v0 offset:29696
	ds_read_b64_tr_b16 v[122:123], v0 offset:30208
	s_waitcnt lgkmcnt(8)
	v_mfma_f32_32x32x16_bf16 v[48:63], v[152:155], v[136:139], v[48:63]
	v_add_f32_e32 v10, v94, v10
	v_add_f32_e32 v10, v95, v10
	v_add_f32_e32 v10, v64, v10
	v_add_f32_e32 v10, v65, v10
	v_cvt_pk_bf16_f32 v142, v92, v93
	v_cvt_pk_bf16_f32 v143, v94, v95
	ds_read_b64_tr_b16 v[136:137], v0 offset:26624
	ds_read_b64_tr_b16 v[138:139], v0 offset:27136
	v_add_f32_e32 v10, v66, v10
	v_add_f32_e32 v10, v67, v10
	v_add_f32_e32 v10, v68, v10
	v_add_f32_e32 v10, v69, v10
	v_cvt_pk_bf16_f32 v132, v64, v65
	v_cvt_pk_bf16_f32 v133, v66, v67
	ds_read_b64_tr_b16 v[124:125], v0 offset:30720
	ds_read_b64_tr_b16 v[126:127], v0 offset:31232
	v_add_f32_e32 v10, v70, v10
	v_add_f32_e32 v10, v71, v10
	v_add_f32_e32 v10, v72, v10
	v_add_f32_e32 v10, v73, v10
	v_cvt_pk_bf16_f32 v134, v68, v69
	v_cvt_pk_bf16_f32 v135, v70, v71
	ds_read_b64_tr_b16 v[116:117], v0 offset:27648
	ds_read_b64_tr_b16 v[118:119], v0 offset:28160
	v_add_f32_e32 v10, v74, v10
	v_add_f32_e32 v10, v75, v10
	v_add_f32_e32 v10, v76, v10
	v_add_f32_e32 v14, v77, v10
	v_cvt_pk_bf16_f32 v128, v72, v73
	v_cvt_pk_bf16_f32 v129, v74, v75
	ds_read_b64_tr_b16 v[10:11], v0 offset:31744
	ds_read_b64_tr_b16 v[12:13], v0 offset:32256
	v_add_f32_e32 v0, v78, v14
	v_add_f32_e32 v0, v79, v0
	v_cvt_pk_bf16_f32 v130, v76, v77
	v_cvt_pk_bf16_f32 v131, v78, v79
	v_or_b32_e32 v15, 0xe0, v188
	v_or_b32_e32 v14, 0xc0, v188
	v_cmp_le_i32_e32 vcc, v15, v191
	v_add_f32_e32 v0, v196, v0
	s_nop 0
	v_cndmask_b32_e32 v48, v243, v48, vcc
	v_cmp_lt_i32_e32 vcc, v14, v191
	s_nop 1
	v_cndmask_b32_e32 v65, v243, v97, vcc
	v_cmp_le_i32_e32 vcc, v14, v191
	v_or_b32_e32 v14, 0xe1, v188
	s_nop 0
	v_cndmask_b32_e32 v64, v243, v96, vcc
	v_cmp_le_i32_e32 vcc, v14, v191
	v_or_b32_e32 v14, 0xc2, v188
	v_max_f32_e32 v15, v64, v64
	v_cndmask_b32_e32 v49, v243, v49, vcc
	v_cmp_le_i32_e32 vcc, v14, v191
	v_or_b32_e32 v14, 0xe2, v188
	s_nop 0
	v_cndmask_b32_e32 v66, v243, v98, vcc
	v_cmp_le_i32_e32 vcc, v14, v191
	v_or_b32_e32 v14, 0xc3, v188
	s_nop 0
	v_cndmask_b32_e32 v50, v243, v50, vcc
	v_cmp_le_i32_e32 vcc, v14, v191
	v_or_b32_e32 v14, 0xe3, v188
	s_nop 0
	v_cndmask_b32_e32 v67, v243, v99, vcc
	v_cmp_le_i32_e32 vcc, v14, v191
	v_or_b32_e32 v14, 0xc8, v188
	s_nop 0
	v_cndmask_b32_e32 v51, v243, v51, vcc
	v_cmp_le_i32_e32 vcc, v14, v191
	v_or_b32_e32 v14, 0xe8, v188
	s_nop 0
	v_cndmask_b32_e32 v68, v243, v100, vcc
	v_cmp_le_i32_e32 vcc, v14, v191
	v_or_b32_e32 v14, 0xc9, v188
	s_nop 0
	v_cndmask_b32_e32 v52, v243, v52, vcc
	v_cmp_le_i32_e32 vcc, v14, v191
	v_or_b32_e32 v14, 0xe9, v188
	s_nop 0
	v_cndmask_b32_e32 v69, v243, v101, vcc
	v_cmp_le_i32_e32 vcc, v14, v191
	v_or_b32_e32 v14, 0xca, v188
	s_nop 0
	v_cndmask_b32_e32 v53, v243, v53, vcc
	v_cmp_le_i32_e32 vcc, v14, v191
	v_or_b32_e32 v14, 0xea, v188
	s_nop 0
	v_cndmask_b32_e32 v70, v243, v102, vcc
	v_cmp_le_i32_e32 vcc, v14, v191
	v_or_b32_e32 v14, 0xcb, v188
	s_nop 0
	v_cndmask_b32_e32 v54, v243, v54, vcc
	v_cmp_le_i32_e32 vcc, v14, v191
	v_or_b32_e32 v14, 0xeb, v188
	s_nop 0
	v_cndmask_b32_e32 v71, v243, v103, vcc
	v_cmp_le_i32_e32 vcc, v14, v191
	v_or_b32_e32 v14, 0xd0, v188
	s_nop 0
	v_cndmask_b32_e32 v55, v243, v55, vcc
	v_cmp_le_i32_e32 vcc, v14, v191
	v_or_b32_e32 v14, 0xf0, v188
	s_nop 0
	v_cndmask_b32_e32 v72, v243, v104, vcc
	v_cmp_le_i32_e32 vcc, v14, v191
	v_or_b32_e32 v14, 0xd1, v188
	s_nop 0
	v_cndmask_b32_e32 v56, v243, v56, vcc
	v_cmp_le_i32_e32 vcc, v14, v191
	v_or_b32_e32 v14, 0xf1, v188
	s_nop 0
	v_cndmask_b32_e32 v73, v243, v105, vcc
	v_cmp_le_i32_e32 vcc, v14, v191
	v_or_b32_e32 v14, 0xd2, v188
	s_nop 0
	v_cndmask_b32_e32 v57, v243, v57, vcc
	v_cmp_le_i32_e32 vcc, v14, v191
	v_or_b32_e32 v14, 0xf2, v188
	s_nop 0
	v_cndmask_b32_e32 v74, v243, v106, vcc
	v_cmp_le_i32_e32 vcc, v14, v191
	v_or_b32_e32 v14, 0xd3, v188
	s_nop 0
	v_cndmask_b32_e32 v58, v243, v58, vcc
	v_cmp_le_i32_e32 vcc, v14, v191
	v_or_b32_e32 v14, 0xf3, v188
	s_nop 0
	v_cndmask_b32_e32 v75, v243, v107, vcc
	v_cmp_le_i32_e32 vcc, v14, v191
	v_or_b32_e32 v14, 0xd8, v188
	s_nop 0
	v_cndmask_b32_e32 v59, v243, v59, vcc
	v_cmp_le_i32_e32 vcc, v14, v191
	v_or_b32_e32 v14, 0xf8, v188
	s_nop 0
	v_cndmask_b32_e32 v76, v243, v108, vcc
	v_cmp_le_i32_e32 vcc, v14, v191
	v_or_b32_e32 v14, 0xd9, v188
	s_nop 0
	v_cndmask_b32_e32 v60, v243, v60, vcc
	v_cmp_le_i32_e32 vcc, v14, v191
	v_or_b32_e32 v14, 0xf9, v188
	s_nop 0
	v_cndmask_b32_e32 v77, v243, v109, vcc
	v_cmp_le_i32_e32 vcc, v14, v191
	v_or_b32_e32 v14, 0xda, v188
	s_nop 0
	v_cndmask_b32_e32 v61, v243, v61, vcc
	v_cmp_le_i32_e32 vcc, v14, v191
	v_or_b32_e32 v14, 0xfa, v188
	s_nop 0
	v_cndmask_b32_e32 v78, v243, v110, vcc
	v_cmp_le_i32_e32 vcc, v14, v191
	v_or_b32_e32 v14, 0xdb, v188
	s_nop 0
	v_cndmask_b32_e32 v62, v243, v62, vcc
	v_cmp_le_i32_e32 vcc, v14, v191
	v_or_b32_e32 v14, 0xfb, v188
	s_nop 0
	v_cndmask_b32_e32 v79, v243, v111, vcc
	v_cmp_le_i32_e32 vcc, v14, v191
	v_max_f32_e32 v14, v65, v65
	v_max_f32_e32 v14, v15, v14
	v_max3_f32 v15, v66, v67, v49
	v_max3_f32 v14, v14, v48, v50
	v_max3_f32 v14, v14, v51, v68
	v_max3_f32 v15, v15, v70, v71
	v_max3_f32 v14, v14, v69, v52
	v_max3_f32 v15, v15, v54, v55
	v_max3_f32 v14, v14, v53, v72
	v_max3_f32 v15, v15, v74, v75
	v_max3_f32 v14, v14, v73, v56
	v_max3_f32 v15, v15, v58, v59
	v_cndmask_b32_e32 v63, v243, v63, vcc
	v_max3_f32 v14, v14, v57, v76
	v_max3_f32 v15, v15, v78, v79
	v_max3_f32 v14, v14, v77, v60
	v_max3_f32 v15, v15, v62, v63
	v_max3_f32 v14, v14, v61, v15
	v_mov_b32_e32 v15, v14
	s_nop 1
	v_permlane32_swap_b32_e32 v14, v15
	v_max_f32_e32 v14, v14, v15
	v_cmp_lt_f32_e32 vcc, s58, v14
	s_cmp_lg_u64 vcc, 0
	s_cselect_b64 s[4:5], -1, 0
	s_cbranch_vccnz .LBB0_630

; __device__ __forceinline__ unsigned xb_add(unsigned* p, unsigned v) { return __hip_atomic_fetch_add(p, v, __ATOMIC_RELAXED, __HIP_MEMORY_SCOPE_AGENT); }
; __device__ __forceinline__ void xcd_barrier(const XcdBarrier& b) {
;     asm volatile("s_waitcnt vmcnt(0)" ::: "memory");
;     __syncthreads();
;     if (threadIdx.x == 0) {
;         unsigned* bar = b.bar;
;         __builtin_amdgcn_s_waitcnt(0);
;         unsigned nloc = b.st[0], nx = b.st[1];
;         if (nloc == 0u) { xcd_barrier_complete(bar, b.x, nloc, nx); b.st[0] = nloc; b.st[1] = nx; }
;         const unsigned old = xb_add(&bar[XB_XSUB(b.x)], 1u);
;         const unsigned gen = old / nloc;
.LBB0_633:
	s_nop 0
	s_nop 0
	s_nop 0
	s_nop 0
	s_nop 0
	s_nop 0
	s_nop 0
	s_nop 0
	s_nop 0
	s_nop 0
	s_nop 0
	s_nop 0
	s_nop 0
	s_nop 0
	s_nop 0
	s_nop 0
	s_nop 0
	s_nop 0
	s_nop 0
	s_nop 0
	s_nop 0
	s_nop 0
	s_nop 0
	s_mov_b64 s[6:7], s[0:1]
	s_getreg_b32 s2, hwreg(HW_REG_XCC_ID, 0, 4)
	s_waitcnt vmcnt(0)
	s_barrier
	s_mov_b64 s[4:5], exec
	v_readlane_b32 s8, v255, 0
	v_readlane_b32 s9, v255, 1
	s_and_b64 s[8:9], s[4:5], s[8:9]
	v_readlane_b32 s41, v255, 10
	s_movk_i32 s42, 0x1000
	s_mov_b64 s[48:49], 0x1200
	s_mov_b32 s62, 0x3c800000
	s_mov_b64 exec, s[8:9]
	s_cbranch_execz .LBB0_685
	v_readlane_b32 s3, v255, 2
	s_load_dwordx2 s[6:7], s[6:7], 0x118
	s_waitcnt vmcnt(0) expcnt(0) lgkmcnt(0)
	v_mov_b32_e32 v0, s3
	ds_read_b32 v3, v0
	v_readlane_b32 s3, v255, 3
	s_and_b32 s2, s2, 15
	s_waitcnt lgkmcnt(0)
	v_cmp_ne_u32_e32 vcc, 0, v3
	v_mov_b32_e32 v0, s3
	ds_read_b32 v0, v0
	s_cbranch_vccnz .LBB0_649
	s_add_u32 s8, s6, 0x1000
	s_addc_u32 s9, s7, 0
	s_add_u32 s10, s6, 0x1100
	s_addc_u32 s11, s7, 0
	s_add_u32 s12, s6, 0x1200
	s_addc_u32 s13, s7, 0
	s_add_u32 s14, s6, 0x1300
	s_addc_u32 s15, s7, 0
	s_mov_b32 s3, 1
	s_branch .LBB0_637
